# phase 2: half of the workgroups run their GLA unit before the rope pass and half after it, so that the rope stream overlaps the other half's unit (on top of the reordered phase 3)
# speedup vs baseline: 1.0110x; 1.0020x over previous
.LBB0_131:
	s_and_b64 vcc, exec, s[0:1]
	s_cbranch_vccz .LBB0_164
	s_cmp_gt_i32 s57, 0
	s_mov_b64 s[40:41], -1
	s_cbranch_scc0 .LBB0_164
	s_cmp_gt_i32 s57, 1
	s_mov_b64 s[42:43], -1
	s_cbranch_scc0 .LBB0_163
	v_readlane_b32 s32, v249, 25
	s_nop 0
	s_bfe_u32 s32, s32, 0x10006
.Lph2_rstart:
	v_mov_b32_e32 v0, v216
	v_readlane_b32 s0, v252, 37
	s_nop 1
	v_add_u32_e32 v36, s0, v0
	s_mov_b32 s0, 0x80000
	v_cmp_gt_i32_e32 vcc, s0, v36
	s_cmp_eq_u32 s32, 1
	s_cselect_b64 vcc, 0, vcc
	s_and_saveexec_b64 s[0:1], vcc
	s_mov_b32 s12, 0x6dc9c883
	s_mov_b32 s14, 0x19d195e7
	s_mov_b32 s16, 0xe5870a9
	s_mov_b32 s18, 0x185ebce3
	s_mov_b32 s22, 0x912545c4
	s_mov_b32 s24, 0x3cfe9378
	s_mov_b32 s26, 0xc4a3df88
	s_mov_b32 s30, 0x4317ad85
	s_mov_b32 s13, 0x3fc45f30
	s_mov_b32 s15, 0x3f9f9ac0
	s_mov_b32 s17, 0x3f7883ec
	s_mov_b32 s19, 0x3f53042d
	s_mov_b32 s23, 0x3f2d8066
	s_mov_b32 s25, 0x3f06e254
	s_mov_b32 s27, 0x3ee1c040
	s_mov_b32 s31, 0x3ebb89df
	s_movk_i32 s34, 0x1000
	s_movk_i32 s35, 0x7000
	s_movk_i32 s40, 0x8c
	s_movk_i32 s42, 0x100
	s_movk_i32 s43, 0x4000
	v_readlane_b32 s8, v254, 2
	v_readlane_b32 s9, v254, 3
	s_cbranch_execz .LBB0_149
	v_readlane_b32 s2, v252, 43
	s_nop 1
	v_lshl_add_u32 v58, v0, 6, s2
	s_mov_b64 s[2:3], 0
	s_branch .LBB0_137

.LBB0_149:
	s_or_b64 exec, exec, s[0:1]
	v_readlane_b32 s0, v249, 8
	v_readlane_b32 s1, v249, 9
	s_movk_i32 s27, 0x80
	s_mov_b32 s30, 0xbfb8aa3b
	s_mov_b32 s31, 0x3f317217
	s_mov_b32 s41, 0x7f800000
	s_andn2_b64 vcc, exec, s[0:1]
	s_mov_b32 s19, 0x400000
	s_cmp_eq_u32 s32, 2
	s_cbranch_scc1 .LBB0_162
	s_cbranch_vccnz .Lph2_gdone
	v_readlane_b32 s0, v254, 36
	v_readlane_b32 s1, v254, 37
	s_mov_b32 s22, s0
	s_ashr_i32 s23, s0, 31
	v_readlane_b32 s4, v254, 8
	s_lshl_b64 s[0:1], s[22:23], 15
	v_readlane_b32 s14, v254, 18
	v_readlane_b32 s15, v254, 19
	s_add_u32 s2, s14, s0
	s_mov_b32 s0, s22
	v_readlane_b32 s5, v254, 9
	v_readlane_b32 s6, v254, 10
	v_readlane_b32 s7, v254, 11
	v_readlane_b32 s8, v254, 12
	v_readlane_b32 s9, v254, 13
	v_readlane_b32 s10, v254, 14
	v_readlane_b32 s11, v254, 15
	v_readlane_b32 s12, v254, 16
	v_readlane_b32 s13, v254, 17
	v_readlane_b32 s16, v254, 20
	v_readlane_b32 s17, v254, 21
	v_readlane_b32 s18, v254, 22
	v_readlane_b32 s19, v254, 23
	s_addc_u32 s3, s15, s1
	v_writelane_b32 v254, s0, 36
	s_lshl_b32 s4, s22, 9
	s_nop 0
	v_writelane_b32 v254, s1, 37
	v_readlane_b32 s0, v249, 5
	s_mov_b32 s22, s0
	s_branch .LBB0_152

.Lph2_gdone:
	s_cmp_eq_u32 s32, 1
	s_cbranch_scc0 .LBB0_162
	s_mov_b32 s32, 2
	s_branch .Lph2_rstart
